# v034 + 64-byte alignment (.p2align 6) of the 19 innermost MFMA loop heads (GEMM K-loops and attention tile loops); instruction stream otherwise unchanged
# speedup vs baseline: 1.0085x; 1.0010x over previous
;     __device__ __forceinline__ bool next(int i, pg8::Unit& u) const { const int L = i * G + c; if (L >= 64) return false; u.pm = L; u.pn = L >> 5; return true; }
; template <class Epi, class Sched, bool ALIGN_EPI = false, bool SP2 = false>
; __device__ __forceinline__ void gemm_phase(PG8_LAS unsigned char* lds, const Gemm g, const Sched& S, const Epi& E, const int wv) {
;     ...
;         const bool has_next = S.next(ui + 1, nxt);
;         const char* nA = has_next ? (const char*)g.A + (size_t)nxt.pm * tstepA : cA; const char* nB = has_next ? (const char*)g.Bt + (size_t)nxt.pn * tstepB : cB;
;         for (int t = 0; t < nt; t += 2) {
;             const bool last = (t == nt - 2);
;             const char* a1 = cA + (size_t)(t + 1) * kstep;
;             const char* a2 = last ? nA : cA + (size_t)(t + 2) * kstep; const char* b2 = last ? nB : cB + (size_t)(t + 2) * kstep;
;     ...
;         for (int a = 0; a < 2; ++a)
; #pragma unroll
;             for (int b = 0; b < 2; ++b)
; #pragma unroll
;                 for (int m = 0; m < 4; ++m)
; #pragma unroll
;                     for (int n = 0; n < 2; ++n) acc[a][b][m][n] = (f32x4){0.f, 0.f, 0.f, 0.f};
.LBB0_207:
	s_ashr_i32 s59, s58, 31
	s_lshl_b64 s[60:61], s[58:59], 19
	s_add_u32 s60, s33, s60
	s_addc_u32 s61, s34, s61
	s_and_b64 s[62:63], s[42:43], exec
	s_cselect_b32 s5, s61, s41
	s_cselect_b32 s7, s60, s40
	s_ashr_i32 s57, s56, 31
	s_lshl_b64 s[62:63], s[56:57], 19
	s_add_u32 s62, s35, s62
	s_addc_u32 s63, s36, s63
	s_and_b64 s[64:65], s[42:43], exec
	s_cselect_b32 s57, s63, s45
	s_cselect_b32 s59, s62, s44
	s_add_u32 s40, s40, 0x40080
	s_addc_u32 s41, s41, 0
	s_add_u32 s66, s44, 0x100
	v_mov_b32_e32 v0, 0
	s_addc_u32 s67, s45, 0
	s_mov_b32 s68, -2
	v_mov_b32_e32 v1, v0
	v_mov_b32_e32 v2, v0
	v_mov_b32_e32 v3, v0
	v_mov_b32_e32 v4, v0
	v_mov_b32_e32 v5, v0
	v_mov_b32_e32 v6, v0
	v_mov_b32_e32 v7, v0
	v_mov_b32_e32 v16, v0
	v_mov_b32_e32 v17, v0
	v_mov_b32_e32 v18, v0
	v_mov_b32_e32 v19, v0
	v_mov_b32_e32 v20, v0
	v_mov_b32_e32 v21, v0
	v_mov_b32_e32 v22, v0
	v_mov_b32_e32 v23, v0
	v_mov_b32_e32 v32, v0
	v_mov_b32_e32 v33, v0
	v_mov_b32_e32 v34, v0
	v_mov_b32_e32 v35, v0
	v_mov_b32_e32 v36, v0
	v_mov_b32_e32 v37, v0
	v_mov_b32_e32 v38, v0
	v_mov_b32_e32 v39, v0
	v_mov_b32_e32 v48, v0
	v_mov_b32_e32 v49, v0
	v_mov_b32_e32 v50, v0
	v_mov_b32_e32 v51, v0
	v_mov_b32_e32 v52, v0
	v_mov_b32_e32 v53, v0
	v_mov_b32_e32 v54, v0
	v_mov_b32_e32 v55, v0
	v_mov_b32_e32 v8, v0
	v_mov_b32_e32 v9, v0
	v_mov_b32_e32 v10, v0
	v_mov_b32_e32 v11, v0
	v_mov_b32_e32 v12, v0
	v_mov_b32_e32 v13, v0
	v_mov_b32_e32 v14, v0
	v_mov_b32_e32 v15, v0
	v_mov_b32_e32 v24, v0
	v_mov_b32_e32 v25, v0
	v_mov_b32_e32 v26, v0
	v_mov_b32_e32 v27, v0
	v_mov_b32_e32 v28, v0
	v_mov_b32_e32 v29, v0
	v_mov_b32_e32 v30, v0
	v_mov_b32_e32 v31, v0
	v_mov_b32_e32 v40, v0
	v_mov_b32_e32 v41, v0
	v_mov_b32_e32 v42, v0
	v_mov_b32_e32 v43, v0
	v_mov_b32_e32 v44, v0
	v_mov_b32_e32 v45, v0
	v_mov_b32_e32 v46, v0
	v_mov_b32_e32 v47, v0
	v_mov_b32_e32 v56, v0
	v_mov_b32_e32 v57, v0
	v_mov_b32_e32 v58, v0
	v_mov_b32_e32 v59, v0
	v_mov_b32_e32 v60, v0
	v_mov_b32_e32 v61, v0
	v_mov_b32_e32 v62, v0
	v_mov_b32_e32 v63, v0
	v_mov_b32_e32 v64, v0
	v_mov_b32_e32 v65, v0
	v_mov_b32_e32 v66, v0
	v_mov_b32_e32 v67, v0
	v_mov_b32_e32 v68, v0
	v_mov_b32_e32 v69, v0
	v_mov_b32_e32 v70, v0
	v_mov_b32_e32 v71, v0
	v_mov_b32_e32 v80, v0
	v_mov_b32_e32 v81, v0
	v_mov_b32_e32 v82, v0
	v_mov_b32_e32 v83, v0
	v_mov_b32_e32 v84, v0
	v_mov_b32_e32 v85, v0
	v_mov_b32_e32 v86, v0
	v_mov_b32_e32 v87, v0
	v_mov_b32_e32 v96, v0
	v_mov_b32_e32 v97, v0
	v_mov_b32_e32 v98, v0
	v_mov_b32_e32 v99, v0
	v_mov_b32_e32 v100, v0
	v_mov_b32_e32 v101, v0
	v_mov_b32_e32 v102, v0
	v_mov_b32_e32 v103, v0
	v_mov_b32_e32 v116, v0
	v_mov_b32_e32 v117, v0
	v_mov_b32_e32 v118, v0
	v_mov_b32_e32 v119, v0
	v_mov_b32_e32 v120, v0
	v_mov_b32_e32 v121, v0
	v_mov_b32_e32 v122, v0
	v_mov_b32_e32 v123, v0
	v_mov_b32_e32 v72, v0
	v_mov_b32_e32 v73, v0
	v_mov_b32_e32 v74, v0
	v_mov_b32_e32 v75, v0
	v_mov_b32_e32 v76, v0
	v_mov_b32_e32 v77, v0
	v_mov_b32_e32 v78, v0
	v_mov_b32_e32 v79, v0
	v_mov_b32_e32 v88, v0
	v_mov_b32_e32 v89, v0
	v_mov_b32_e32 v90, v0
	v_mov_b32_e32 v91, v0
	v_mov_b32_e32 v92, v0
	v_mov_b32_e32 v93, v0
	v_mov_b32_e32 v94, v0
	v_mov_b32_e32 v95, v0
	v_mov_b32_e32 v104, v0
	v_mov_b32_e32 v105, v0
	v_mov_b32_e32 v106, v0
	v_mov_b32_e32 v107, v0
	v_mov_b32_e32 v108, v0
	v_mov_b32_e32 v109, v0
	v_mov_b32_e32 v110, v0
	v_mov_b32_e32 v111, v0
	v_mov_b32_e32 v124, v0
	v_mov_b32_e32 v125, v0
	v_mov_b32_e32 v126, v0
	v_mov_b32_e32 v127, v0
	v_mov_b32_e32 v128, v0
	v_mov_b32_e32 v129, v0
	v_mov_b32_e32 v130, v0
	v_mov_b32_e32 v131, v0
	.p2align 6

;     __device__ __forceinline__ bool next(int i, pg8::Unit& u) const { const int L = i * G + c; if (L >= 64) return false; u.pm = L; u.pn = L >> 5; return true; }
; template <class Epi, class Sched, bool ALIGN_EPI = false, bool SP2 = false>
; __device__ __forceinline__ void gemm_phase(PG8_LAS unsigned char* lds, const Gemm g, const Sched& S, const Epi& E, const int wv) {
;     ...
;         const bool has_next = S.next(ui + 1, nxt);
;         const char* nA = has_next ? (const char*)g.A + (size_t)nxt.pm * tstepA : cA; const char* nB = has_next ? (const char*)g.Bt + (size_t)nxt.pn * tstepB : cB;
;         for (int t = 0; t < nt; t += 2) {
;             const bool last = (t == nt - 2);
;             const char* a1 = cA + (size_t)(t + 1) * kstep;
;             const char* a2 = last ? nA : cA + (size_t)(t + 2) * kstep; const char* b2 = last ? nB : cB + (size_t)(t + 2) * kstep;
;     ...
;         for (int a = 0; a < 2; ++a)
; #pragma unroll
;             for (int b = 0; b < 2; ++b)
; #pragma unroll
;                 for (int m = 0; m < 4; ++m)
; #pragma unroll
;                     for (int n = 0; n < 2; ++n) acc[a][b][m][n] = (f32x4){0.f, 0.f, 0.f, 0.f};
.LBB0_328:
	s_ashr_i32 s31, s30, 31
	s_lshl_b64 s[38:39], s[30:31], 19
	s_add_u32 s38, s33, s38
	s_addc_u32 s39, s34, s39
	s_and_b64 s[44:45], s[42:43], exec
	s_cselect_b32 s31, s39, s5
	s_cselect_b32 s46, s38, s4
	s_ashr_i32 s21, s20, 31
	s_lshl_b64 s[44:45], s[20:21], 19
	s_add_u32 s48, s35, s44
	s_addc_u32 s49, s36, s45
	s_and_b64 s[44:45], s[42:43], exec
	s_cselect_b32 s21, s49, s41
	s_cselect_b32 s47, s48, s40
	s_add_u32 s4, s4, 0x40080
	s_addc_u32 s5, s5, 0
	s_add_u32 s65, s40, 0x100
	v_mov_b32_e32 v0, 0
	s_addc_u32 s66, s41, 0
	s_mov_b32 s67, -2
	v_mov_b32_e32 v1, v0
	v_mov_b32_e32 v2, v0
	s_waitcnt lgkmcnt(0)
	v_mov_b32_e32 v3, v0
	v_mov_b32_e32 v4, v0
	v_mov_b32_e32 v5, v0
	v_mov_b32_e32 v6, v0
	v_mov_b32_e32 v7, v0
	v_mov_b32_e32 v40, v0
	v_mov_b32_e32 v41, v0
	v_mov_b32_e32 v42, v0
	v_mov_b32_e32 v43, v0
	v_mov_b32_e32 v48, v0
	v_mov_b32_e32 v49, v0
	v_mov_b32_e32 v50, v0
	v_mov_b32_e32 v51, v0
	v_mov_b32_e32 v64, v0
	v_mov_b32_e32 v65, v0
	v_mov_b32_e32 v66, v0
	v_mov_b32_e32 v67, v0
	v_mov_b32_e32 v68, v0
	v_mov_b32_e32 v69, v0
	v_mov_b32_e32 v70, v0
	v_mov_b32_e32 v71, v0
	v_mov_b32_e32 v80, v0
	v_mov_b32_e32 v81, v0
	v_mov_b32_e32 v82, v0
	v_mov_b32_e32 v83, v0
	v_mov_b32_e32 v84, v0
	v_mov_b32_e32 v85, v0
	v_mov_b32_e32 v86, v0
	v_mov_b32_e32 v87, v0
	v_mov_b32_e32 v8, v0
	v_mov_b32_e32 v9, v0
	v_mov_b32_e32 v10, v0
	v_mov_b32_e32 v11, v0
	v_mov_b32_e32 v12, v0
	v_mov_b32_e32 v13, v0
	v_mov_b32_e32 v14, v0
	v_mov_b32_e32 v15, v0
	v_mov_b32_e32 v56, v0
	v_mov_b32_e32 v57, v0
	v_mov_b32_e32 v58, v0
	v_mov_b32_e32 v59, v0
	v_mov_b32_e32 v60, v0
	v_mov_b32_e32 v61, v0
	v_mov_b32_e32 v62, v0
	v_mov_b32_e32 v63, v0
	v_mov_b32_e32 v72, v0
	v_mov_b32_e32 v73, v0
	v_mov_b32_e32 v74, v0
	v_mov_b32_e32 v75, v0
	v_mov_b32_e32 v76, v0
	v_mov_b32_e32 v77, v0
	v_mov_b32_e32 v78, v0
	v_mov_b32_e32 v79, v0
	v_mov_b32_e32 v88, v0
	v_mov_b32_e32 v89, v0
	v_mov_b32_e32 v90, v0
	v_mov_b32_e32 v91, v0
	v_mov_b32_e32 v92, v0
	v_mov_b32_e32 v93, v0
	v_mov_b32_e32 v94, v0
	v_mov_b32_e32 v95, v0
	v_mov_b32_e32 v96, v0
	v_mov_b32_e32 v97, v0
	v_mov_b32_e32 v98, v0
	v_mov_b32_e32 v99, v0
	v_mov_b32_e32 v100, v0
	v_mov_b32_e32 v101, v0
	v_mov_b32_e32 v102, v0
	v_mov_b32_e32 v103, v0
	v_mov_b32_e32 v118, v0
	v_mov_b32_e32 v119, v0
	v_mov_b32_e32 v120, v0
	v_mov_b32_e32 v121, v0
	v_mov_b32_e32 v122, v0
	v_mov_b32_e32 v123, v0
	v_mov_b32_e32 v124, v0
	v_mov_b32_e32 v125, v0
	v_mov_b32_e32 v134, v0
	v_mov_b32_e32 v135, v0
	v_mov_b32_e32 v136, v0
	v_mov_b32_e32 v137, v0
	v_mov_b32_e32 v138, v0
	v_mov_b32_e32 v139, v0
	v_mov_b32_e32 v140, v0
	v_mov_b32_e32 v141, v0
	v_mov_b32_e32 v16, v0
	v_mov_b32_e32 v17, v0
	v_mov_b32_e32 v18, v0
	v_mov_b32_e32 v19, v0
	v_mov_b32_e32 v20, v0
	v_mov_b32_e32 v21, v0
	v_mov_b32_e32 v22, v0
	v_mov_b32_e32 v23, v0
	v_mov_b32_e32 v104, v0
	v_mov_b32_e32 v105, v0
	v_mov_b32_e32 v106, v0
	v_mov_b32_e32 v107, v0
	v_mov_b32_e32 v108, v0
	v_mov_b32_e32 v109, v0
	v_mov_b32_e32 v110, v0
	v_mov_b32_e32 v111, v0
	v_mov_b32_e32 v126, v0
	v_mov_b32_e32 v127, v0
	v_mov_b32_e32 v128, v0
	v_mov_b32_e32 v129, v0
	v_mov_b32_e32 v130, v0
	v_mov_b32_e32 v131, v0
	v_mov_b32_e32 v132, v0
	v_mov_b32_e32 v133, v0
	v_mov_b32_e32 v142, v0
	v_mov_b32_e32 v143, v0
	v_mov_b32_e32 v144, v0
	v_mov_b32_e32 v145, v0
	v_mov_b32_e32 v146, v0
	v_mov_b32_e32 v147, v0
	v_mov_b32_e32 v148, v0
	v_mov_b32_e32 v149, v0
	v_mov_b32_e32 v24, v0
	v_mov_b32_e32 v25, v0
	v_mov_b32_e32 v26, v0
	v_mov_b32_e32 v27, v0
	v_mov_b32_e32 v52, v0
	v_mov_b32_e32 v53, v0
	v_mov_b32_e32 v54, v0
	v_mov_b32_e32 v55, v0
	.p2align 6

;     __device__ __forceinline__ bool next(int i, pg8::Unit& u) const { const int L = i * G + c; if (L >= 64) return false; u.pm = L; u.pn = L >> 5; return true; }
; template <class Epi, class Sched, bool ALIGN_EPI = false, bool SP2 = false>
; __device__ __forceinline__ void gemm_phase(PG8_LAS unsigned char* lds, const Gemm g, const Sched& S, const Epi& E, const int wv) {
;     ...
;         const bool has_next = S.next(ui + 1, nxt);
;         const char* nA = has_next ? (const char*)g.A + (size_t)nxt.pm * tstepA : cA; const char* nB = has_next ? (const char*)g.Bt + (size_t)nxt.pn * tstepB : cB;
;         for (int t = 0; t < nt; t += 2) {
;             const bool last = (t == nt - 2);
;             const char* a1 = cA + (size_t)(t + 1) * kstep;
;             const char* a2 = last ? nA : cA + (size_t)(t + 2) * kstep; const char* b2 = last ? nB : cB + (size_t)(t + 2) * kstep;
;     ...
;         for (int a = 0; a < 2; ++a)
; #pragma unroll
;             for (int b = 0; b < 2; ++b)
; #pragma unroll
;                 for (int m = 0; m < 4; ++m)
; #pragma unroll
;                     for (int n = 0; n < 2; ++n) acc[a][b][m][n] = (f32x4){0.f, 0.f, 0.f, 0.f};
.LBB0_503:
	s_add_i32 s43, s43, 1
	s_mov_b64 s[30:31], s[10:11]
	s_mov_b32 s10, s6
	s_mov_b32 s45, s6
	s_mul_i32 s6, s43, s12
	s_mov_b32 s1, s44
	s_mov_b32 s46, s44
	s_add_i32 s44, s6, s2
	s_cmp_lt_i32 s44, 64
	s_cselect_b64 s[20:21], -1, 0
	s_ashr_i32 s6, s44, 5
	s_mov_b64 s[4:5], s[8:9]
	s_and_b64 s[8:9], s[20:21], exec
	s_cselect_b32 s8, s44, s1
	s_cselect_b32 s10, s6, s10
	s_ashr_i32 s9, s8, 31
	s_lshl_b64 s[8:9], s[8:9], 19
	s_add_u32 s8, s0, s8
	s_addc_u32 s9, s13, s9
	s_and_b64 s[38:39], s[20:21], exec
	s_cselect_b32 s47, s9, s5
	s_cselect_b32 s48, s8, s4
	s_ashr_i32 s11, s10, 31
	s_lshl_b64 s[10:11], s[10:11], 20
	s_add_u32 s10, s23, s10
	s_addc_u32 s11, s27, s11
	s_and_b64 s[38:39], s[20:21], exec
	s_cselect_b32 s49, s11, s31
	s_cselect_b32 s50, s10, s30
	s_add_u32 s4, s4, 0x40080
	s_addc_u32 s5, s5, 0
	s_add_u32 s51, s30, 0x100
	v_mov_b32_e32 v0, 0
	s_addc_u32 s52, s31, 0
	s_mov_b32 s53, -2
	v_mov_b32_e32 v1, v0
	v_mov_b32_e32 v2, v0
	v_mov_b32_e32 v3, v0
	v_mov_b32_e32 v4, v0
	v_mov_b32_e32 v5, v0
	v_mov_b32_e32 v6, v0
	v_mov_b32_e32 v7, v0
	v_mov_b32_e32 v16, v0
	v_mov_b32_e32 v17, v0
	v_mov_b32_e32 v18, v0
	v_mov_b32_e32 v19, v0
	v_mov_b32_e32 v20, v0
	v_mov_b32_e32 v21, v0
	v_mov_b32_e32 v22, v0
	v_mov_b32_e32 v23, v0
	v_mov_b32_e32 v32, v0
	v_mov_b32_e32 v33, v0
	v_mov_b32_e32 v34, v0
	v_mov_b32_e32 v35, v0
	v_mov_b32_e32 v36, v0
	v_mov_b32_e32 v37, v0
	v_mov_b32_e32 v38, v0
	v_mov_b32_e32 v39, v0
	v_mov_b32_e32 v48, v0
	v_mov_b32_e32 v49, v0
	v_mov_b32_e32 v50, v0
	v_mov_b32_e32 v51, v0
	v_mov_b32_e32 v52, v0
	v_mov_b32_e32 v53, v0
	v_mov_b32_e32 v54, v0
	v_mov_b32_e32 v55, v0
	v_mov_b32_e32 v8, v0
	v_mov_b32_e32 v9, v0
	v_mov_b32_e32 v10, v0
	v_mov_b32_e32 v11, v0
	v_mov_b32_e32 v12, v0
	v_mov_b32_e32 v13, v0
	v_mov_b32_e32 v14, v0
	v_mov_b32_e32 v15, v0
	v_mov_b32_e32 v24, v0
	v_mov_b32_e32 v25, v0
	v_mov_b32_e32 v26, v0
	v_mov_b32_e32 v27, v0
	v_mov_b32_e32 v28, v0
	v_mov_b32_e32 v29, v0
	v_mov_b32_e32 v30, v0
	v_mov_b32_e32 v31, v0
	v_mov_b32_e32 v40, v0
	v_mov_b32_e32 v41, v0
	v_mov_b32_e32 v42, v0
	v_mov_b32_e32 v43, v0
	v_mov_b32_e32 v44, v0
	v_mov_b32_e32 v45, v0
	v_mov_b32_e32 v46, v0
	v_mov_b32_e32 v47, v0
	v_mov_b32_e32 v56, v0
	v_mov_b32_e32 v57, v0
	v_mov_b32_e32 v58, v0
	v_mov_b32_e32 v59, v0
	v_mov_b32_e32 v60, v0
	v_mov_b32_e32 v61, v0
	v_mov_b32_e32 v62, v0
	v_mov_b32_e32 v63, v0
	v_mov_b32_e32 v64, v0
	v_mov_b32_e32 v65, v0
	v_mov_b32_e32 v66, v0
	v_mov_b32_e32 v67, v0
	v_mov_b32_e32 v68, v0
	v_mov_b32_e32 v69, v0
	v_mov_b32_e32 v70, v0
	v_mov_b32_e32 v71, v0
	v_mov_b32_e32 v80, v0
	v_mov_b32_e32 v81, v0
	v_mov_b32_e32 v82, v0
	v_mov_b32_e32 v83, v0
	v_mov_b32_e32 v84, v0
	v_mov_b32_e32 v85, v0
	v_mov_b32_e32 v86, v0
	v_mov_b32_e32 v87, v0
	v_mov_b32_e32 v96, v0
	v_mov_b32_e32 v97, v0
	v_mov_b32_e32 v98, v0
	v_mov_b32_e32 v99, v0
	v_mov_b32_e32 v100, v0
	v_mov_b32_e32 v101, v0
	v_mov_b32_e32 v102, v0
	v_mov_b32_e32 v103, v0
	v_mov_b32_e32 v116, v0
	v_mov_b32_e32 v117, v0
	v_mov_b32_e32 v118, v0
	v_mov_b32_e32 v119, v0
	v_mov_b32_e32 v120, v0
	v_mov_b32_e32 v121, v0
	v_mov_b32_e32 v122, v0
	v_mov_b32_e32 v123, v0
	v_mov_b32_e32 v72, v0
	v_mov_b32_e32 v73, v0
	v_mov_b32_e32 v74, v0
	v_mov_b32_e32 v75, v0
	v_mov_b32_e32 v76, v0
	v_mov_b32_e32 v77, v0
	v_mov_b32_e32 v78, v0
	v_mov_b32_e32 v79, v0
	v_mov_b32_e32 v88, v0
	v_mov_b32_e32 v89, v0
	v_mov_b32_e32 v90, v0
	v_mov_b32_e32 v91, v0
	v_mov_b32_e32 v92, v0
	v_mov_b32_e32 v93, v0
	v_mov_b32_e32 v94, v0
	v_mov_b32_e32 v95, v0
	v_mov_b32_e32 v104, v0
	v_mov_b32_e32 v105, v0
	v_mov_b32_e32 v106, v0
	v_mov_b32_e32 v107, v0
	v_mov_b32_e32 v108, v0
	v_mov_b32_e32 v109, v0
	v_mov_b32_e32 v110, v0
	v_mov_b32_e32 v111, v0
	v_mov_b32_e32 v124, v0
	v_mov_b32_e32 v125, v0
	v_mov_b32_e32 v126, v0
	v_mov_b32_e32 v127, v0
	v_mov_b32_e32 v128, v0
	v_mov_b32_e32 v129, v0
	v_mov_b32_e32 v130, v0
	v_mov_b32_e32 v131, v0
	.p2align 6

; template <bool HAS_POST, class MaskF>
; __device__ __forceinline__ void attn_run(LAS unsigned char* lds, const bf16* Kg, const bf16* Vg, int pitch, int t0, int t1,
;                                          const bf16x8 (&qr)[4], f32x16& o0, f32x16& o1, f32x16& o2, MaskF& mf, const int wv) {
;     ...
;     ACtx cx; cx.lds = lds; cx.kroff = r32 * 144 + hi * 16;
;     { const int gi = lane & 15, dsub = (lane >> 4) & 1, q4 = gi >> 2;
;       cx.vro0 = ATT_V0 + (4 * hi + q4) * 128 + (((0 + dsub) ^ (q4 & 2)) * 32) + (gi & 3) * 8;
;       cx.vro1 = ATT_V0 + (4 * hi + q4) * 128 + (((2 + dsub) ^ (q4 & 2)) * 32) + (gi & 3) * 8; }
;     if (wv >= 4) __builtin_amdgcn_s_setprio(1);
;     const short one_b = (r32 == 0) ? (short)0x3F80 : (short)0;
;     const bf16x8 ones = (bf16x8){one_b, one_b, one_b, one_b, one_b, one_b, one_b, one_b};
; __device__ __forceinline__ void nsa_unit(const int wv, LAS unsigned char* lds, int b, int g, int c, const bf16* Y, const bf16* KCMP, const bf16* VCMP, const float* gates, bf16* OG) {
;     ...
;         CmpMask mf; mf.tabs = tabs; mf.hi = hi; mf.imp = imph + (hr * 64 + tq) * 65;
;         const bf16* Kg = KCMP + (size_t)(b * 4 + g) * 256 * 64; const bf16* Vg = VCMP + (size_t)(b * 4 + g) * 256 * 64;
;         f32x16 o0 = zero16(), o1 = zero16(), o2 = zero16();
;         attn_run<true>(lds, Kg, Vg, 64, 0, nct, qr, o0, o1, o2, mf, wv);
.LBB0_648:
	v_and_b32_e32 v51, 31, v4
	v_cmp_eq_u32_e32 vcc, 0, v51
	v_bfe_u32 v52, v4, 5, 1
	v_bfe_u32 v54, v4, 4, 1
	v_lshrrev_b32_e32 v2, 2, v50
	v_lshlrev_b32_e32 v3, 5, v50
	v_lshlrev_b32_e32 v162, 6, v1
	v_cndmask_b32_e32 v58, 0, v249, vcc
	s_mov_b32 s1, 0x5040100
	v_lshlrev_b32_e32 v53, 4, v52
	v_and_b32_e32 v55, 0x180, v3
	v_lshlrev_b32_e32 v3, 3, v4
	v_bitop3_b32 v2, v54, v2, 2 bitop3:0x72
	v_perm_b32 v96, v58, v58, s1
	s_movk_i32 s1, 0x90
	v_or_b32_e32 v49, v162, v49
	v_and_b32_e32 v56, 24, v3
	v_lshlrev_b32_e32 v57, 5, v2
	v_lshlrev_b32_e32 v112, 2, v160
	v_mad_u32_u24 v164, v51, s1, v53
	v_lshl_or_b32 v51, v52, 9, v55
	v_lshlrev_b32_e32 v50, 3, v50
	v_add_u32_e32 v48, v49, v48
	s_movk_i32 s1, 0x104
	v_or3_b32 v165, v51, v57, v56
	v_and_or_b32 v50, v50, 64, v51
	v_lshlrev_b32_e32 v51, 5, v54
	v_mad_u64_u32 v[156:157], s[4:5], v48, s1, v[112:113]
	s_mov_b32 s16, 2
	v_mov_b32_e32 v1, v0
	v_mov_b32_e32 v2, v0
	v_mov_b32_e32 v3, v0
	v_mov_b32_e32 v4, v0
	v_mov_b32_e32 v5, v0
	v_mov_b32_e32 v6, v0
	v_mov_b32_e32 v7, v0
	v_mov_b32_e32 v8, v0
	v_mov_b32_e32 v9, v0
	v_mov_b32_e32 v10, v0
	v_mov_b32_e32 v11, v0
	v_mov_b32_e32 v12, v0
	v_mov_b32_e32 v13, v0
	v_mov_b32_e32 v14, v0
	v_mov_b32_e32 v15, v0
	v_mov_b32_e32 v17, v16
	v_mov_b32_e32 v18, v16
	v_mov_b32_e32 v19, v16
	v_mov_b32_e32 v20, v16
	v_mov_b32_e32 v21, v16
	v_mov_b32_e32 v22, v16
	v_mov_b32_e32 v23, v16
	v_mov_b32_e32 v24, v16
	v_mov_b32_e32 v25, v16
	v_mov_b32_e32 v26, v16
	v_mov_b32_e32 v27, v16
	v_mov_b32_e32 v28, v16
	v_mov_b32_e32 v29, v16
	v_mov_b32_e32 v30, v16
	v_mov_b32_e32 v31, v16
	v_mov_b32_e32 v33, v32
	v_mov_b32_e32 v34, v32
	v_mov_b32_e32 v35, v32
	v_mov_b32_e32 v36, v32
	v_mov_b32_e32 v37, v32
	v_mov_b32_e32 v38, v32
	v_mov_b32_e32 v39, v32
	v_mov_b32_e32 v40, v32
	v_mov_b32_e32 v41, v32
	v_mov_b32_e32 v42, v32
	v_mov_b32_e32 v43, v32
	v_mov_b32_e32 v44, v32
	v_mov_b32_e32 v45, v32
	v_mov_b32_e32 v46, v32
	v_mov_b32_e32 v47, v32
	s_add_i32 s17, s0, -3
	v_mov_b32_e32 v97, v96
	v_mov_b32_e32 v98, v96
	v_mov_b32_e32 v99, v96
	v_or3_b32 v166, v50, v51, v56
	v_lshl_add_u32 v157, v160, 6, v242
	v_or_b32_e32 v167, 22, v160
	v_or_b32_e32 v168, 0x5b, v112
	s_branch .LBB0_650
	.p2align 6

; __device__ __forceinline__ int crow(int r, int hi) { return (r & 3) + 8 * (r >> 2) + 4 * hi; }
; template <bool HAS_POST, class MaskF>
; __device__ __forceinline__ void attn_run(LAS unsigned char* lds, const bf16* Kg, const bf16* Vg, int pitch, int t0, int t1,
;                                          const bf16x8 (&qr)[4], f32x16& o0, f32x16& o1, f32x16& o2, MaskF& mf, const int wv) {
;     ...
;     ACtx cx; cx.lds = lds; cx.kroff = r32 * 144 + hi * 16;
;     { const int gi = lane & 15, dsub = (lane >> 4) & 1, q4 = gi >> 2;
;       cx.vro0 = ATT_V0 + (4 * hi + q4) * 128 + (((0 + dsub) ^ (q4 & 2)) * 32) + (gi & 3) * 8;
;       cx.vro1 = ATT_V0 + (4 * hi + q4) * 128 + (((2 + dsub) ^ (q4 & 2)) * 32) + (gi & 3) * 8; }
;     if (wv >= 4) __builtin_amdgcn_s_setprio(1);
;     const short one_b = (r32 == 0) ? (short)0x3F80 : (short)0;
;     const bf16x8 ones = (bf16x8){one_b, one_b, one_b, one_b, one_b, one_b, one_b, one_b};
;     __device__ __forceinline__ void apply(int t, f32x16& p0, f32x16& p1) const {
;         if (t == c) {
; #pragma unroll
;             for (int r = 0; r < 16; ++r) { const int kv = crow(r, hi); if (kv > tq) p0[r] = NEGBIG; if (kv + 32 > tq) p1[r] = NEGBIG; }
;         }
.LBB0_709:
	v_and_b32_e32 v48, 31, v1
	v_cmp_eq_u32_e32 vcc, 0, v48
	v_mul_u32_u24_e32 v49, 0x90, v48
	s_mov_b32 s1, 0x5040100
	v_cndmask_b32_e32 v48, 0, v249, vcc
	v_perm_b32 v96, v48, v48, s1
	v_or_b32_e32 v48, 32, v112
	v_cmp_gt_u32_e64 s[46:47], v48, v113
	v_or_b32_e32 v48, 33, v112
	v_cmp_gt_u32_e64 s[50:51], v48, v113
	v_or_b32_e32 v48, 2, v112
	v_cmp_gt_u32_e64 s[52:53], v48, v113
	v_or_b32_e32 v48, 34, v112
	v_cmp_gt_u32_e64 s[54:55], v48, v113
	v_or_b32_e32 v48, 3, v112
	v_cmp_gt_u32_e64 s[56:57], v48, v113
	v_or_b32_e32 v48, 35, v112
	v_cmp_gt_u32_e64 s[58:59], v48, v113
	v_or_b32_e32 v48, 8, v112
	v_cmp_gt_u32_e64 s[60:61], v48, v113
	v_or_b32_e32 v48, 40, v112
	v_cmp_gt_u32_e64 s[62:63], v48, v113
	v_or_b32_e32 v48, 9, v112
	v_cmp_gt_u32_e64 s[64:65], v48, v113
	v_or_b32_e32 v48, 41, v112
	v_cmp_gt_u32_e64 s[66:67], v48, v113
	v_or_b32_e32 v48, 10, v112
	v_cmp_gt_u32_e64 s[68:69], v48, v113
	v_or_b32_e32 v48, 42, v112
	v_cmp_gt_u32_e64 s[70:71], v48, v113
	v_or_b32_e32 v48, 11, v112
	v_cmp_gt_u32_e64 s[72:73], v48, v113
	v_or_b32_e32 v48, 43, v112
	v_cmp_gt_u32_e64 s[74:75], v48, v113
	v_or_b32_e32 v48, 16, v112
	v_cmp_gt_u32_e64 s[76:77], v48, v113
	v_or_b32_e32 v48, 48, v112
	v_cmp_gt_u32_e64 s[78:79], v48, v113
	v_or_b32_e32 v48, 17, v112
	v_cmp_gt_u32_e64 s[80:81], v48, v113
	v_or_b32_e32 v48, 49, v112
	v_cmp_gt_u32_e64 s[82:83], v48, v113
	v_or_b32_e32 v48, 18, v112
	v_cmp_gt_u32_e64 s[84:85], v48, v113
	v_or_b32_e32 v48, 50, v112
	v_cmp_gt_u32_e64 s[86:87], v48, v113
	v_or_b32_e32 v48, 19, v112
	v_cmp_gt_u32_e64 s[88:89], v48, v113
	v_or_b32_e32 v48, 51, v112
	v_cmp_gt_u32_e64 s[90:91], v48, v113
	v_or_b32_e32 v48, 24, v112
	v_cmp_gt_u32_e64 s[92:93], v48, v113
	v_or_b32_e32 v48, 56, v112
	v_cmp_gt_u32_e64 s[94:95], v48, v113
	v_or_b32_e32 v48, 25, v112
	v_cmp_gt_u32_e64 s[96:97], v48, v113
	v_or_b32_e32 v48, 57, v112
	v_cmp_gt_u32_e64 s[6:7], v48, v113
	v_or_b32_e32 v48, 26, v112
	v_cmp_gt_u32_e64 s[8:9], v48, v113
	v_or_b32_e32 v48, 58, v112
	v_bfe_u32 v3, v1, 5, 1
	v_bfe_u32 v4, v1, 4, 1
	v_lshrrev_b32_e32 v5, 2, v2
	v_lshlrev_b32_e32 v2, 5, v2
	v_lshlrev_b32_e32 v1, 3, v1
	v_cmp_gt_u32_e64 s[10:11], v48, v113
	v_or_b32_e32 v48, 27, v112
	v_lshlrev_b32_e32 v50, 4, v3
	v_lshlrev_b32_e32 v51, 9, v3
	v_and_b32_e32 v52, 0x180, v2
	v_and_or_b32 v2, v5, 2, v4
	v_and_b32_e32 v161, 24, v1
	v_bitop3_b32 v1, v4, v5, 2 bitop3:0x72
	v_cmp_gt_u32_e64 s[12:13], v48, v113
	v_or_b32_e32 v48, 59, v112
	s_sub_i32 s36, 0, s3
	v_lshlrev_b32_e32 v160, 5, v2
	v_lshlrev_b32_e32 v162, 5, v1
	v_mov_b32_e32 v17, v16
	v_mov_b32_e32 v18, v16
	v_mov_b32_e32 v19, v16
	v_mov_b32_e32 v20, v16
	v_mov_b32_e32 v21, v16
	v_mov_b32_e32 v22, v16
	v_mov_b32_e32 v23, v16
	v_mov_b32_e32 v24, v16
	v_mov_b32_e32 v25, v16
	v_mov_b32_e32 v26, v16
	v_mov_b32_e32 v27, v16
	v_mov_b32_e32 v28, v16
	v_mov_b32_e32 v29, v16
	v_mov_b32_e32 v30, v16
	v_mov_b32_e32 v31, v16
	v_mov_b32_e32 v1, v0
	v_mov_b32_e32 v2, v0
	v_mov_b32_e32 v3, v0
	v_mov_b32_e32 v4, v0
	v_mov_b32_e32 v5, v0
	v_mov_b32_e32 v6, v0
	v_mov_b32_e32 v7, v0
	v_mov_b32_e32 v8, v0
	v_mov_b32_e32 v9, v0
	v_mov_b32_e32 v10, v0
	v_mov_b32_e32 v11, v0
	v_mov_b32_e32 v12, v0
	v_mov_b32_e32 v13, v0
	v_mov_b32_e32 v14, v0
	v_mov_b32_e32 v15, v0
	v_mov_b32_e32 v33, v32
	v_mov_b32_e32 v34, v32
	v_mov_b32_e32 v35, v32
	v_mov_b32_e32 v36, v32
	v_mov_b32_e32 v37, v32
	v_mov_b32_e32 v38, v32
	v_mov_b32_e32 v39, v32
	v_mov_b32_e32 v40, v32
	v_mov_b32_e32 v41, v32
	v_mov_b32_e32 v42, v32
	v_mov_b32_e32 v43, v32
	v_mov_b32_e32 v44, v32
	v_mov_b32_e32 v45, v32
	v_mov_b32_e32 v46, v32
	v_mov_b32_e32 v47, v32
	v_add3_u32 v163, 0, v49, v50
	v_mov_b32_e32 v97, v96
	v_mov_b32_e32 v98, v96
	v_mov_b32_e32 v99, v96
	v_add3_u32 v164, 0, v52, v51
	v_cmp_gt_u32_e64 s[44:45], v112, v113
	v_cmp_lt_u32_e64 s[48:49], v112, v113
	v_cmp_gt_u32_e64 s[14:15], v48, v113
	v_cmp_le_u32_e64 s[16:17], v48, v113
	s_add_u32 s37, s36, 63
	s_add_u32 s2, s36, 62
	s_mov_b64 s[4:5], 0
	.p2align 6

; template <bool HAS_POST, class MaskF>
; __device__ __forceinline__ void attn_run(LAS unsigned char* lds, const bf16* Kg, const bf16* Vg, int pitch, int t0, int t1,
;                                          const bf16x8 (&qr)[4], f32x16& o0, f32x16& o1, f32x16& o2, MaskF& mf, const int wv) {
;     ...
;     ACtx cx; cx.lds = lds; cx.kroff = r32 * 144 + hi * 16;
;     { const int gi = lane & 15, dsub = (lane >> 4) & 1, q4 = gi >> 2;
;       cx.vro0 = ATT_V0 + (4 * hi + q4) * 128 + (((0 + dsub) ^ (q4 & 2)) * 32) + (gi & 3) * 8;
;       cx.vro1 = ATT_V0 + (4 * hi + q4) * 128 + (((2 + dsub) ^ (q4 & 2)) * 32) + (gi & 3) * 8; }
;     if (wv >= 4) __builtin_amdgcn_s_setprio(1);
;     const short one_b = (r32 == 0) ? (short)0x3F80 : (short)0;
;     const bf16x8 ones = (bf16x8){one_b, one_b, one_b, one_b, one_b, one_b, one_b, one_b};
; __device__ __forceinline__ void nsa_unit(const int wv, LAS unsigned char* lds, int b, int g, int c, const bf16* Y, const bf16* KCMP, const bf16* VCMP, const float* gates, bf16* OG) {
;     ...
;     {
;         WinMask mf; mf.c = c; mf.tq = tq; mf.hi = hi;
;         const bf16* Kg = Y + (size_t)b * T * NSA_LDY + 1536 + g * 64;
;         f32x16 o0 = zero16(), o1 = zero16(), o2 = zero16();
;         attn_run<false>(lds, Kg, Kg + 256, NSA_LDY, (c > 8) ? c - 8 : 0, c + 1, qr, o0, o1, o2, mf, wv);
.LBB0_744:
	v_and_b32_e32 v2, 31, v0
	v_bfe_u32 v3, v0, 5, 1
	v_bfe_u32 v6, v0, 4, 1
	v_lshrrev_b32_e32 v7, 2, v1
	v_lshlrev_b32_e32 v0, 3, v0
	v_and_b32_e32 v205, 24, v0
	v_bitop3_b32 v0, v6, v7, 2 bitop3:0x72
	v_cmp_eq_u32_e32 vcc, 0, v2
	v_lshlrev_b32_e32 v1, 5, v1
	v_lshlrev_b32_e32 v206, 5, v0
	v_cndmask_b32_e32 v0, 0, v249, vcc
	s_mov_b32 s1, 0x5040100
	v_mul_u32_u24_e32 v4, 0x90, v2
	v_lshlrev_b32_e32 v5, 4, v3
	v_lshlrev_b32_e32 v3, 9, v3
	v_and_b32_e32 v1, 0x180, v1
	v_and_or_b32 v8, v7, 2, v6
	v_perm_b32 v148, v0, v0, s1
	s_sub_i32 s41, s36, s38
	v_lshlrev_b32_e32 v204, 5, v8
	s_mov_b32 s3, 0
	v_add3_u32 v207, 0, v4, v5
	v_mov_b32_e32 v149, v148
	v_mov_b32_e32 v150, v148
	v_mov_b32_e32 v151, v148
	v_add3_u32 v208, 0, v1, v3
	s_add_i32 s36, s41, 62
	s_add_i32 s39, s41, 63
	s_add_i32 s40, s41, 0x46
	s_addk_i32 s41, 0x47
	v_mov_b32_e32 v0, v202
	v_mov_b32_e32 v1, v202
	v_mov_b32_e32 v2, v202
	v_mov_b32_e32 v3, v202
	v_mov_b32_e32 v4, v202
	v_mov_b32_e32 v5, v202
	v_mov_b32_e32 v6, v202
	v_mov_b32_e32 v7, v202
	v_mov_b32_e32 v8, v202
	v_mov_b32_e32 v9, v202
	v_mov_b32_e32 v10, v202
	v_mov_b32_e32 v11, v202
	v_mov_b32_e32 v12, v202
	v_mov_b32_e32 v13, v202
	v_mov_b32_e32 v14, v202
	v_mov_b32_e32 v15, v202
	v_mov_b32_e32 v16, v33
	v_mov_b32_e32 v17, v33
	v_mov_b32_e32 v18, v33
	v_mov_b32_e32 v19, v33
	v_mov_b32_e32 v20, v33
	v_mov_b32_e32 v21, v33
	v_mov_b32_e32 v22, v33
	v_mov_b32_e32 v23, v33
	v_mov_b32_e32 v24, v33
	v_mov_b32_e32 v25, v33
	v_mov_b32_e32 v26, v33
	v_mov_b32_e32 v27, v33
	v_mov_b32_e32 v28, v33
	v_mov_b32_e32 v29, v33
	v_mov_b32_e32 v30, v33
	v_mov_b32_e32 v31, v33
	v_mov_b32_e32 v34, v32
	v_mov_b32_e32 v35, v32
	v_mov_b32_e32 v36, v32
	v_mov_b32_e32 v37, v32
	v_mov_b32_e32 v38, v32
	v_mov_b32_e32 v39, v32
	v_mov_b32_e32 v40, v32
	v_mov_b32_e32 v41, v32
	v_mov_b32_e32 v42, v32
	v_mov_b32_e32 v43, v32
	v_mov_b32_e32 v44, v32
	v_mov_b32_e32 v45, v32
	v_mov_b32_e32 v46, v32
	v_mov_b32_e32 v47, v32
	v_mov_b32_e32 v48, v32
	v_mov_b32_e32 v49, v32
	s_branch .LBB0_746
	.p2align 6

; template <bool HAS_POST, class MaskF>
; __device__ __forceinline__ void attn_run(LAS unsigned char* lds, const bf16* Kg, const bf16* Vg, int pitch, int t0, int t1,
;                                          const bf16x8 (&qr)[4], f32x16& o0, f32x16& o1, f32x16& o2, MaskF& mf, const int wv) {
;     ...
;     for (int ts = t0; ts < t1; ts += 2) {
;         const int cur = ((ts - t0) >> 1) & 1;
;         const bool more = (ts + 2 < t1), more2 = (ts + 3 < t1);
;         if (more) { kp += 2 * tstride; kreg0 = *(const v4u*)kp; vp += 2 * tstride; vreg0 = *(const v4u*)vp;
;             if (more2) { kreg1 = *(const v4u*)(kp + tstride); vreg1 = *(const v4u*)(vp + tstride); } }
; #pragma unroll
;         for (int j = 0; j < 2; ++j) {
;             const int t = ts + j;
;             if (t >= t1) break;
;             if (mf.skip(t)) continue;
;     __device__ __forceinline__ bool skip(int t) const { const int nb = t >> 2; if (nb >= qb) return 64 * (t & 3) > wq0 + 31; return !__any((int)((sel >> nb) & 1u)); }
.LBB0_798:
	s_lshr_b32 s40, s1, 2
	s_cmp_ge_u32 s40, s3
	s_cselect_b64 s[30:31], -1, 0
	s_cmp_lt_u32 s40, s3
	s_mov_b64 s[10:11], -1
	s_cbranch_scc1 .LBB0_812
	s_sub_i32 s0, s34, 64
	s_and_b32 s0, s0, 0x80
	v_readlane_b32 s8, v254, 2
	s_cmp_gt_u32 s0, s8
	s_cselect_b64 s[8:9], -1, 0
	s_lshl_b32 s0, 1, s40
	s_cbranch_execz .LBB0_813
	.p2align 6

; template <bool HAS_POST, class MaskF>
; __device__ __forceinline__ void attn_run(LAS unsigned char* lds, const bf16* Kg, const bf16* Vg, int pitch, int t0, int t1,
;                                          const bf16x8 (&qr)[4], f32x16& o0, f32x16& o1, f32x16& o2, MaskF& mf, const int wv) {
;     ...
;         for (int j = 0; j < 2; ++j) {
;             const int t = ts + j;
;             if (t >= t1) break;
;             if (mf.skip(t)) continue;
;     __device__ __forceinline__ bool skip(int t) const { const int nb = t >> 2; if (nb >= qb) return 64 * (t & 3) > wq0 + 31; return !__any((int)((sel >> nb) & 1u)); }
.LBB0_816:
	s_cmp_ge_u32 s35, s22
	s_cbranch_scc1 .LBB0_832
	v_cndmask_b32_e64 v48, 0, 1, s[30:31]
	v_cmp_ne_u32_e64 s[8:9], 1, v48
	s_andn2_b64 vcc, exec, s[30:31]
	s_mov_b64 s[10:11], -1
	s_cbranch_vccnz .LBB0_830
	s_and_b32 s1, s34, 0xc0
	v_readlane_b32 s12, v254, 2
	s_cmp_gt_u32 s1, s12
	s_cselect_b64 s[12:13], -1, 0
	v_and_b32_e32 v168, s0, v159
	v_cmp_ne_u32_e64 s[10:11], 0, v168
	s_cbranch_execz .LBB0_831
	.p2align 6

; template <bool HAS_POST, class MaskF>
; __device__ __forceinline__ void attn_run(LAS unsigned char* lds, const bf16* Kg, const bf16* Vg, int pitch, int t0, int t1,
;                                          const bf16x8 (&qr)[4], f32x16& o0, f32x16& o1, f32x16& o2, MaskF& mf, const int wv) {
;     ...
;     ACtx cx; cx.lds = lds; cx.kroff = r32 * 144 + hi * 16;
;     { const int gi = lane & 15, dsub = (lane >> 4) & 1, q4 = gi >> 2;
;       cx.vro0 = ATT_V0 + (4 * hi + q4) * 128 + (((0 + dsub) ^ (q4 & 2)) * 32) + (gi & 3) * 8;
;       cx.vro1 = ATT_V0 + (4 * hi + q4) * 128 + (((2 + dsub) ^ (q4 & 2)) * 32) + (gi & 3) * 8; }
;     if (wv >= 4) __builtin_amdgcn_s_setprio(1);
;     const short one_b = (r32 == 0) ? (short)0x3F80 : (short)0;
;     const bf16x8 ones = (bf16x8){one_b, one_b, one_b, one_b, one_b, one_b, one_b, one_b};
; __device__ __forceinline__ void nsa_unit(const int wv, LAS unsigned char* lds, int b, int g, int c, const bf16* Y, const bf16* KCMP, const bf16* VCMP, const float* gates, bf16* OG) {
;     ...
;     {
;         int ncnt = 4 * c + 3; if (ncnt > 255) ncnt = 255; const int nct = (ncnt + 63) >> 6;
;         CmpMask mf; mf.tabs = tabs; mf.hi = hi; mf.imp = imph + (hr * 64 + tq) * 65;
;         const bf16* Kg = KCMP + (size_t)(b * 4 + g) * 256 * 64; const bf16* Vg = VCMP + (size_t)(b * 4 + g) * 256 * 64;
;         f32x16 o0 = zero16(), o1 = zero16(), o2 = zero16();
;         attn_run<true>(lds, Kg, Vg, 64, 0, nct, qr, o0, o1, o2, mf, wv);
.LBB0_849:
	v_and_b32_e32 v0, 31, v4
	v_cmp_eq_u32_e32 vcc, 0, v0
	v_mul_u32_u24_e32 v6, 0x90, v0
	s_mov_b32 s0, 0x5040100
	v_cndmask_b32_e32 v0, 0, v249, vcc
	v_bfe_u32 v1, v4, 5, 1
	v_bfe_u32 v8, v4, 4, 1
	v_lshrrev_b32_e32 v9, 2, v5
	v_lshlrev_b32_e32 v5, 5, v5
	v_lshlrev_b32_e32 v4, 3, v4
	v_perm_b32 v98, v0, v0, s0
	v_add3_u32 v0, v153, v3, v2
	s_movk_i32 s0, 0x104
	v_lshlrev_b32_e32 v7, 4, v1
	v_lshlrev_b32_e32 v1, 9, v1
	v_and_b32_e32 v5, 0x180, v5
	v_and_or_b32 v10, v9, 2, v8
	v_and_b32_e32 v165, 24, v4
	v_bitop3_b32 v4, v8, v9, 2 bitop3:0x72
	v_mul_lo_u32 v0, v0, s0
	s_mov_b32 s16, 2
	v_lshlrev_b32_e32 v164, 5, v10
	v_lshlrev_b32_e32 v166, 5, v4
	s_mov_b32 s17, 0
	v_add3_u32 v167, 0, v6, v7
	v_mov_b32_e32 v99, v98
	v_mov_b32_e32 v100, v98
	v_mov_b32_e32 v101, v98
	v_add3_u32 v168, 0, v5, v1
	v_lshlrev_b32_e32 v169, 2, v159
	v_add_u32_e32 v170, 0, v0
	v_lshl_add_u32 v171, v159, 6, v242
	v_or_b32_e32 v172, 20, v159
	v_mov_b32_e32 v34, v32
	v_mov_b32_e32 v35, v32
	v_mov_b32_e32 v36, v32
	v_mov_b32_e32 v37, v32
	v_mov_b32_e32 v38, v32
	v_mov_b32_e32 v39, v32
	v_mov_b32_e32 v40, v32
	v_mov_b32_e32 v41, v32
	v_mov_b32_e32 v42, v32
	v_mov_b32_e32 v43, v32
	v_mov_b32_e32 v44, v32
	v_mov_b32_e32 v45, v32
	v_mov_b32_e32 v46, v32
	v_mov_b32_e32 v47, v32
	v_mov_b32_e32 v48, v32
	v_mov_b32_e32 v49, v32
	v_mov_b32_e32 v0, v162
	v_mov_b32_e32 v1, v162
	v_mov_b32_e32 v2, v162
	v_mov_b32_e32 v3, v162
	v_mov_b32_e32 v4, v162
	v_mov_b32_e32 v5, v162
	v_mov_b32_e32 v6, v162
	v_mov_b32_e32 v7, v162
	v_mov_b32_e32 v8, v162
	v_mov_b32_e32 v9, v162
	v_mov_b32_e32 v10, v162
	v_mov_b32_e32 v11, v162
	v_mov_b32_e32 v12, v162
	v_mov_b32_e32 v13, v162
	v_mov_b32_e32 v14, v162
	v_mov_b32_e32 v15, v162
	v_mov_b32_e32 v16, v161
	v_mov_b32_e32 v17, v161
	v_mov_b32_e32 v18, v161
	v_mov_b32_e32 v19, v161
	v_mov_b32_e32 v20, v161
	v_mov_b32_e32 v21, v161
	v_mov_b32_e32 v22, v161
	v_mov_b32_e32 v23, v161
	v_mov_b32_e32 v24, v161
	v_mov_b32_e32 v25, v161
	v_mov_b32_e32 v26, v161
	v_mov_b32_e32 v27, v161
	v_mov_b32_e32 v28, v161
	v_mov_b32_e32 v29, v161
	v_mov_b32_e32 v30, v161
	v_mov_b32_e32 v31, v161
	s_branch .LBB0_851
	.p2align 6

; __device__ __forceinline__ int crow(int r, int hi) { return (r & 3) + 8 * (r >> 2) + 4 * hi; }
; template <bool HAS_POST, class MaskF>
; __device__ __forceinline__ void attn_run(LAS unsigned char* lds, const bf16* Kg, const bf16* Vg, int pitch, int t0, int t1,
;                                          const bf16x8 (&qr)[4], f32x16& o0, f32x16& o1, f32x16& o2, MaskF& mf, const int wv) {
;     ...
;     ACtx cx; cx.lds = lds; cx.kroff = r32 * 144 + hi * 16;
;     { const int gi = lane & 15, dsub = (lane >> 4) & 1, q4 = gi >> 2;
;       cx.vro0 = ATT_V0 + (4 * hi + q4) * 128 + (((0 + dsub) ^ (q4 & 2)) * 32) + (gi & 3) * 8;
;       cx.vro1 = ATT_V0 + (4 * hi + q4) * 128 + (((2 + dsub) ^ (q4 & 2)) * 32) + (gi & 3) * 8; }
;     if (wv >= 4) __builtin_amdgcn_s_setprio(1);
;     const short one_b = (r32 == 0) ? (short)0x3F80 : (short)0;
;     const bf16x8 ones = (bf16x8){one_b, one_b, one_b, one_b, one_b, one_b, one_b, one_b};
;     __device__ __forceinline__ void apply(int t, f32x16& p0, f32x16& p1) const {
;         if (t == c) {
; #pragma unroll
;             for (int r = 0; r < 16; ++r) { const int kv = crow(r, hi); if (kv > tq) p0[r] = NEGBIG; if (kv + 32 > tq) p1[r] = NEGBIG; }
;         }
.LBB0_920:
	v_and_b32_e32 v2, 31, v0
	v_bfe_u32 v3, v0, 5, 1
	v_bfe_u32 v6, v0, 4, 1
	v_lshrrev_b32_e32 v7, 2, v1
	v_lshlrev_b32_e32 v0, 3, v0
	v_and_b32_e32 v164, 24, v0
	v_bitop3_b32 v0, v6, v7, 2 bitop3:0x72
	v_cmp_eq_u32_e32 vcc, 0, v2
	v_lshlrev_b32_e32 v1, 5, v1
	v_lshlrev_b32_e32 v165, 5, v0
	v_cndmask_b32_e32 v0, 0, v249, vcc
	s_mov_b32 s0, 0x5040100
	v_lshlrev_b32_e32 v5, 4, v3
	v_lshlrev_b32_e32 v3, 9, v3
	v_and_b32_e32 v1, 0x180, v1
	v_perm_b32 v98, v0, v0, s0
	v_lshlrev_b32_e32 v0, 2, v159
	v_add3_u32 v167, 0, v1, v3
	v_or_b32_e32 v1, 32, v0
	v_cmp_gt_u32_e64 s[8:9], v1, v158
	v_or_b32_e32 v1, 33, v0
	v_cmp_gt_u32_e64 s[12:13], v1, v158
	v_or_b32_e32 v1, 2, v0
	v_cmp_gt_u32_e64 s[14:15], v1, v158
	v_or_b32_e32 v1, 34, v0
	v_cmp_gt_u32_e64 s[16:17], v1, v158
	v_or_b32_e32 v1, 3, v0
	v_cmp_gt_u32_e64 s[40:41], v1, v158
	v_or_b32_e32 v1, 35, v0
	v_cmp_gt_u32_e64 s[42:43], v1, v158
	v_or_b32_e32 v1, 8, v0
	v_cmp_gt_u32_e64 s[44:45], v1, v158
	v_or_b32_e32 v1, 40, v0
	v_cmp_gt_u32_e64 s[46:47], v1, v158
	v_or_b32_e32 v1, 9, v0
	v_cmp_gt_u32_e64 s[48:49], v1, v158
	v_or_b32_e32 v1, 41, v0
	v_cmp_gt_u32_e64 s[50:51], v1, v158
	v_or_b32_e32 v1, 10, v0
	v_cmp_gt_u32_e64 s[52:53], v1, v158
	v_or_b32_e32 v1, 42, v0
	v_cmp_gt_u32_e64 s[54:55], v1, v158
	v_or_b32_e32 v1, 11, v0
	v_cmp_gt_u32_e64 s[56:57], v1, v158
	v_or_b32_e32 v1, 43, v0
	v_cmp_gt_u32_e64 s[58:59], v1, v158
	v_or_b32_e32 v1, 16, v0
	v_cmp_gt_u32_e64 s[60:61], v1, v158
	v_or_b32_e32 v1, 48, v0
	v_cmp_gt_u32_e64 s[62:63], v1, v158
	v_or_b32_e32 v1, 17, v0
	v_cmp_gt_u32_e64 s[64:65], v1, v158
	v_or_b32_e32 v1, 49, v0
	v_cmp_gt_u32_e64 s[66:67], v1, v158
	v_or_b32_e32 v1, 18, v0
	v_cmp_gt_u32_e64 s[68:69], v1, v158
	v_or_b32_e32 v1, 50, v0
	v_cmp_gt_u32_e64 s[70:71], v1, v158
	v_or_b32_e32 v1, 19, v0
	v_cmp_gt_u32_e64 s[72:73], v1, v158
	v_or_b32_e32 v1, 51, v0
	v_cmp_gt_u32_e64 s[74:75], v1, v158
	v_or_b32_e32 v1, 24, v0
	v_cmp_gt_u32_e64 s[76:77], v1, v158
	v_or_b32_e32 v1, 56, v0
	v_cmp_gt_u32_e64 s[78:79], v1, v158
	v_or_b32_e32 v1, 25, v0
	v_cmp_gt_u32_e64 s[80:81], v1, v158
	v_or_b32_e32 v1, 57, v0
	v_cmp_gt_u32_e64 s[82:83], v1, v158
	v_or_b32_e32 v1, 26, v0
	v_cmp_gt_u32_e64 s[84:85], v1, v158
	v_or_b32_e32 v1, 58, v0
	v_mul_u32_u24_e32 v4, 0x90, v2
	v_and_or_b32 v8, v7, 2, v6
	v_cmp_gt_u32_e64 s[6:7], v0, v158
	v_cmp_lt_u32_e64 s[10:11], v0, v158
	v_cmp_gt_u32_e64 s[86:87], v1, v158
	v_or_b32_e32 v1, 27, v0
	v_or_b32_e32 v0, 59, v0
	v_lshlrev_b32_e32 v163, 5, v8
	v_add3_u32 v166, 0, v4, v5
	v_mov_b32_e32 v99, v98
	v_mov_b32_e32 v100, v98
	v_mov_b32_e32 v101, v98
	v_cmp_gt_u32_e64 s[88:89], v1, v158
	v_cmp_gt_u32_e64 s[90:91], v0, v158
	s_mov_b64 s[4:5], 0
	v_mov_b32_e32 v0, v160
	v_mov_b32_e32 v1, v160
	v_mov_b32_e32 v2, v160
	v_mov_b32_e32 v3, v160
	v_mov_b32_e32 v4, v160
	v_mov_b32_e32 v5, v160
	v_mov_b32_e32 v6, v160
	v_mov_b32_e32 v7, v160
	v_mov_b32_e32 v8, v160
	v_mov_b32_e32 v9, v160
	v_mov_b32_e32 v10, v160
	v_mov_b32_e32 v11, v160
	v_mov_b32_e32 v12, v160
	v_mov_b32_e32 v13, v160
	v_mov_b32_e32 v14, v160
	v_mov_b32_e32 v15, v160
	v_mov_b32_e32 v16, v33
	v_mov_b32_e32 v17, v33
	v_mov_b32_e32 v18, v33
	v_mov_b32_e32 v19, v33
	v_mov_b32_e32 v20, v33
	v_mov_b32_e32 v21, v33
	v_mov_b32_e32 v22, v33
	v_mov_b32_e32 v23, v33
	v_mov_b32_e32 v24, v33
	v_mov_b32_e32 v25, v33
	v_mov_b32_e32 v26, v33
	v_mov_b32_e32 v27, v33
	v_mov_b32_e32 v28, v33
	v_mov_b32_e32 v29, v33
	v_mov_b32_e32 v30, v33
	v_mov_b32_e32 v31, v33
	v_mov_b32_e32 v34, v32
	v_mov_b32_e32 v35, v32
	v_mov_b32_e32 v36, v32
	v_mov_b32_e32 v37, v32
	v_mov_b32_e32 v38, v32
	v_mov_b32_e32 v39, v32
	v_mov_b32_e32 v40, v32
	v_mov_b32_e32 v41, v32
	v_mov_b32_e32 v42, v32
	v_mov_b32_e32 v43, v32
	v_mov_b32_e32 v44, v32
	v_mov_b32_e32 v45, v32
	v_mov_b32_e32 v46, v32
	v_mov_b32_e32 v47, v32
	v_mov_b32_e32 v48, v32
	v_mov_b32_e32 v49, v32
	.p2align 6

; __device__ __forceinline__ int crow(int r, int hi) { return (r & 3) + 8 * (r >> 2) + 4 * hi; }
; template <bool HAS_POST, class MaskF>
; __device__ __forceinline__ void attn_run(LAS unsigned char* lds, const bf16* Kg, const bf16* Vg, int pitch, int t0, int t1,
;                                          const bf16x8 (&qr)[4], f32x16& o0, f32x16& o1, f32x16& o2, MaskF& mf, const int wv) {
;     ...
;     ACtx cx; cx.lds = lds; cx.kroff = r32 * 144 + hi * 16;
;     { const int gi = lane & 15, dsub = (lane >> 4) & 1, q4 = gi >> 2;
;       cx.vro0 = ATT_V0 + (4 * hi + q4) * 128 + (((0 + dsub) ^ (q4 & 2)) * 32) + (gi & 3) * 8;
;       cx.vro1 = ATT_V0 + (4 * hi + q4) * 128 + (((2 + dsub) ^ (q4 & 2)) * 32) + (gi & 3) * 8; }
;     if (wv >= 4) __builtin_amdgcn_s_setprio(1);
;     const short one_b = (r32 == 0) ? (short)0x3F80 : (short)0;
;     const bf16x8 ones = (bf16x8){one_b, one_b, one_b, one_b, one_b, one_b, one_b, one_b};
;     __device__ __forceinline__ void apply(int t, f32x16& p0, f32x16& p1) const {
;         if (t == c) {
; #pragma unroll
;             for (int r = 0; r < 16; ++r) { const int kv = crow(r, hi); if (kv > tq) p0[r] = NEGBIG; if (kv + 32 > tq) p1[r] = NEGBIG; }
;         } else if (t == c - 8) {
; #pragma unroll
;             for (int r = 0; r < 16; ++r) { const int kv = crow(r, hi); if (kv <= tq) p0[r] = NEGBIG; if (kv + 32 <= tq) p1[r] = NEGBIG; }
;         }
.LBB0_958:
	v_and_b32_e32 v2, 31, v0
	v_bfe_u32 v3, v0, 5, 1
	v_bfe_u32 v6, v0, 4, 1
	v_lshrrev_b32_e32 v7, 2, v1
	v_lshlrev_b32_e32 v0, 3, v0
	v_and_b32_e32 v205, 24, v0
	v_bitop3_b32 v0, v6, v7, 2 bitop3:0x72
	v_cmp_eq_u32_e32 vcc, 0, v2
	v_lshlrev_b32_e32 v1, 5, v1
	v_lshlrev_b32_e32 v206, 5, v0
	v_cndmask_b32_e32 v0, 0, v249, vcc
	s_mov_b32 s0, 0x5040100
	v_lshlrev_b32_e32 v5, 4, v3
	v_lshlrev_b32_e32 v3, 9, v3
	v_and_b32_e32 v1, 0x180, v1
	v_perm_b32 v148, v0, v0, s0
	v_lshlrev_b32_e32 v0, 2, v159
	v_add3_u32 v208, 0, v1, v3
	v_or_b32_e32 v1, 32, v0
	v_cmp_gt_u32_e64 s[8:9], v1, v158
	v_or_b32_e32 v1, 33, v0
	v_cmp_gt_u32_e64 s[12:13], v1, v158
	v_or_b32_e32 v1, 2, v0
	v_cmp_gt_u32_e64 s[14:15], v1, v158
	v_or_b32_e32 v1, 34, v0
	v_cmp_gt_u32_e64 s[16:17], v1, v158
	v_or_b32_e32 v1, 3, v0
	v_cmp_gt_u32_e64 s[40:41], v1, v158
	v_or_b32_e32 v1, 35, v0
	v_cmp_gt_u32_e64 s[42:43], v1, v158
	v_or_b32_e32 v1, 8, v0
	v_cmp_gt_u32_e64 s[44:45], v1, v158
	v_or_b32_e32 v1, 40, v0
	v_cmp_gt_u32_e64 s[46:47], v1, v158
	v_or_b32_e32 v1, 9, v0
	v_cmp_gt_u32_e64 s[48:49], v1, v158
	v_or_b32_e32 v1, 41, v0
	v_cmp_gt_u32_e64 s[50:51], v1, v158
	v_or_b32_e32 v1, 10, v0
	v_cmp_gt_u32_e64 s[52:53], v1, v158
	v_or_b32_e32 v1, 42, v0
	v_cmp_gt_u32_e64 s[54:55], v1, v158
	v_or_b32_e32 v1, 11, v0
	v_cmp_gt_u32_e64 s[56:57], v1, v158
	v_or_b32_e32 v1, 43, v0
	v_cmp_gt_u32_e64 s[58:59], v1, v158
	v_or_b32_e32 v1, 16, v0
	v_cmp_gt_u32_e64 s[60:61], v1, v158
	v_or_b32_e32 v1, 48, v0
	v_cmp_gt_u32_e64 s[62:63], v1, v158
	v_or_b32_e32 v1, 17, v0
	v_cmp_gt_u32_e64 s[64:65], v1, v158
	v_or_b32_e32 v1, 49, v0
	v_cmp_gt_u32_e64 s[66:67], v1, v158
	v_or_b32_e32 v1, 18, v0
	v_cmp_gt_u32_e64 s[68:69], v1, v158
	v_or_b32_e32 v1, 50, v0
	v_cmp_gt_u32_e64 s[70:71], v1, v158
	v_or_b32_e32 v1, 19, v0
	v_cmp_gt_u32_e64 s[72:73], v1, v158
	v_or_b32_e32 v1, 51, v0
	v_cmp_gt_u32_e64 s[74:75], v1, v158
	v_or_b32_e32 v1, 24, v0
	v_cmp_gt_u32_e64 s[76:77], v1, v158
	v_or_b32_e32 v1, 56, v0
	v_cmp_gt_u32_e64 s[78:79], v1, v158
	v_or_b32_e32 v1, 25, v0
	v_cmp_gt_u32_e64 s[80:81], v1, v158
	v_or_b32_e32 v1, 57, v0
	v_cmp_gt_u32_e64 s[82:83], v1, v158
	v_or_b32_e32 v1, 26, v0
	v_cmp_gt_u32_e64 s[84:85], v1, v158
	v_or_b32_e32 v1, 58, v0
	v_mul_u32_u24_e32 v4, 0x90, v2
	v_and_or_b32 v8, v7, 2, v6
	v_cmp_gt_u32_e64 s[6:7], v0, v158
	v_cmp_lt_u32_e64 s[10:11], v0, v158
	v_cmp_gt_u32_e64 s[86:87], v1, v158
	v_or_b32_e32 v1, 27, v0
	v_or_b32_e32 v0, 59, v0
	v_lshlrev_b32_e32 v204, 5, v8
	s_mov_b32 s96, 0
	v_add3_u32 v207, 0, v4, v5
	v_mov_b32_e32 v149, v148
	v_mov_b32_e32 v150, v148
	v_mov_b32_e32 v151, v148
	v_cmp_gt_u32_e64 s[88:89], v1, v158
	v_cmp_gt_u32_e64 s[90:91], v0, v158
	v_cmp_le_u32_e64 s[92:93], v0, v158
	v_mov_b32_e32 v0, v202
	v_mov_b32_e32 v1, v202
	v_mov_b32_e32 v2, v202
	v_mov_b32_e32 v3, v202
	v_mov_b32_e32 v4, v202
	v_mov_b32_e32 v5, v202
	v_mov_b32_e32 v6, v202
	v_mov_b32_e32 v7, v202
	v_mov_b32_e32 v8, v202
	v_mov_b32_e32 v9, v202
	v_mov_b32_e32 v10, v202
	v_mov_b32_e32 v11, v202
	v_mov_b32_e32 v12, v202
	v_mov_b32_e32 v13, v202
	v_mov_b32_e32 v14, v202
	v_mov_b32_e32 v15, v202
	v_mov_b32_e32 v16, v33
	v_mov_b32_e32 v17, v33
	v_mov_b32_e32 v18, v33
	v_mov_b32_e32 v19, v33
	v_mov_b32_e32 v20, v33
	v_mov_b32_e32 v21, v33
	v_mov_b32_e32 v22, v33
	v_mov_b32_e32 v23, v33
	v_mov_b32_e32 v24, v33
	v_mov_b32_e32 v25, v33
	v_mov_b32_e32 v26, v33
	v_mov_b32_e32 v27, v33
	v_mov_b32_e32 v28, v33
	v_mov_b32_e32 v29, v33
	v_mov_b32_e32 v30, v33
	v_mov_b32_e32 v31, v33
	v_mov_b32_e32 v34, v32
	v_mov_b32_e32 v35, v32
	v_mov_b32_e32 v36, v32
	v_mov_b32_e32 v37, v32
	v_mov_b32_e32 v38, v32
	v_mov_b32_e32 v39, v32
	v_mov_b32_e32 v40, v32
	v_mov_b32_e32 v41, v32
	v_mov_b32_e32 v42, v32
	v_mov_b32_e32 v43, v32
	v_mov_b32_e32 v44, v32
	v_mov_b32_e32 v45, v32
	v_mov_b32_e32 v46, v32
	v_mov_b32_e32 v47, v32
	v_mov_b32_e32 v48, v32
	v_mov_b32_e32 v49, v32
	s_branch .LBB0_960
	.p2align 6

; template <bool HAS_POST, class MaskF>
; __device__ __forceinline__ void attn_run(LAS unsigned char* lds, const bf16* Kg, const bf16* Vg, int pitch, int t0, int t1,
;                                          const bf16x8 (&qr)[4], f32x16& o0, f32x16& o1, f32x16& o2, MaskF& mf, const int wv) {
;     ...
;     for (int ts = t0; ts < t1; ts += 2) {
;         const int cur = ((ts - t0) >> 1) & 1;
;         const bool more = (ts + 2 < t1), more2 = (ts + 3 < t1);
;         if (more) { kp += 2 * tstride; kreg0 = *(const v4u*)kp; vp += 2 * tstride; vreg0 = *(const v4u*)vp;
;             if (more2) { kreg1 = *(const v4u*)(kp + tstride); vreg1 = *(const v4u*)(vp + tstride); } }
; #pragma unroll
;         for (int j = 0; j < 2; ++j) {
;             const int t = ts + j;
;             if (t >= t1) break;
;             if (mf.skip(t)) continue;
;     __device__ __forceinline__ bool skip(int t) const { const int nb = t >> 2; if (nb >= qb) return 64 * (t & 3) > wq0 + 31; return !__any((int)((sel >> nb) & 1u)); }
.LBB0_1169:
.LBB0_1170:
	s_lshr_b32 s60, s1, 2
	s_cmp_ge_u32 s60, s33
	s_cselect_b64 s[30:31], -1, 0
	s_cmp_lt_u32 s60, s33
	s_mov_b64 s[10:11], -1
	s_cbranch_scc1 .LBB0_1184
	s_sub_i32 s0, s36, 64
	s_and_b32 s0, s0, 0x80
	v_readlane_b32 s8, v254, 2
	s_cmp_gt_u32 s0, s8
	s_cselect_b64 s[8:9], -1, 0
	s_lshl_b32 s0, 1, s60
	s_cbranch_execz .LBB0_1185
	.p2align 6

; template <bool HAS_POST, class MaskF>
; __device__ __forceinline__ void attn_run(LAS unsigned char* lds, const bf16* Kg, const bf16* Vg, int pitch, int t0, int t1,
;                                          const bf16x8 (&qr)[4], f32x16& o0, f32x16& o1, f32x16& o2, MaskF& mf, const int wv) {
;     ...
;         for (int j = 0; j < 2; ++j) {
;             const int t = ts + j;
;             if (t >= t1) break;
;             if (mf.skip(t)) continue;
;     __device__ __forceinline__ bool skip(int t) const { const int nb = t >> 2; if (nb >= qb) return 64 * (t & 3) > wq0 + 31; return !__any((int)((sel >> nb) & 1u)); }
.LBB0_1188:
	s_cmp_ge_u32 s37, s35
	s_cbranch_scc1 .LBB0_1204
	s_andn2_b64 s[8:9], exec, s[30:31]
	s_andn2_b64 vcc, exec, s[30:31]
	s_mov_b64 s[10:11], -1
	s_cbranch_vccnz .LBB0_1202
	s_and_b32 s1, s36, 0xc0
	v_readlane_b32 s12, v254, 2
	s_cmp_gt_u32 s1, s12
	s_cselect_b64 s[12:13], -1, 0
	v_and_b32_e32 v168, s0, v159
	v_cmp_ne_u32_e64 s[10:11], 0, v168
	s_cbranch_execz .LBB0_1203
	.p2align 6

;     __device__ __forceinline__ bool next(int i, pg8::Unit& u) const { const int L = i * G + c; if (L >= 64) return false; u.pm = L; u.pn = L >> 5; return true; }
; template <class Epi, class Sched, bool ALIGN_EPI = false, bool SP2 = false>
; __device__ __forceinline__ void gemm_phase(PG8_LAS unsigned char* lds, const Gemm g, const Sched& S, const Epi& E, const int wv) {
;     ...
;     for (;;) {
;         const bool has_next = S.next(ui + 1, nxt);
;         const char* nA = has_next ? (const char*)g.A + (size_t)nxt.pm * tstepA : cA; const char* nB = has_next ? (const char*)g.Bt + (size_t)nxt.pn * tstepB : cB;
;         for (int t = 0; t < nt; t += 2) {
;             const bool last = (t == nt - 2);
;             const char* a1 = cA + (size_t)(t + 1) * kstep;
;             const char* a2 = last ? nA : cA + (size_t)(t + 2) * kstep; const char* b2 = last ? nB : cB + (size_t)(t + 2) * kstep;
;             const char* a3 = a2 + kstep; const char* b3 = b2 + kstep;
;     ...
; #pragma unroll
;         for (int a = 0; a < 2; ++a)
; #pragma unroll
;             for (int b = 0; b < 2; ++b)
; #pragma unroll
;                 for (int m = 0; m < 4; ++m)
; #pragma unroll
;                     for (int n = 0; n < 2; ++n) acc[a][b][m][n] = (f32x4){0.f, 0.f, 0.f, 0.f};
.LBB0_1280:
	s_ashr_i32 s53, s52, 31
	s_lshl_b64 s[0:1], s[52:53], 19
	s_add_u32 s54, s37, s0
	s_addc_u32 s55, s62, s1
	s_and_b64 s[0:1], s[8:9], exec
	s_cselect_b32 s0, s55, s11
	s_cselect_b32 s5, s54, s10
	s_ashr_i32 s51, s50, 31
	s_lshl_b64 s[56:57], s[50:51], 19
	s_add_u32 s56, s63, s56
	s_addc_u32 s57, s64, s57
	s_and_b64 s[60:61], s[8:9], exec
	s_cselect_b32 s51, s57, s13
	s_cselect_b32 s53, s56, s12
	s_add_u32 s10, s10, 0x40080
	s_addc_u32 s11, s11, 0
	s_add_u32 s59, s12, 0x100
	v_mov_b32_e32 v0, 0
	s_addc_u32 s75, s13, 0
	s_mov_b32 s76, -2
	v_mov_b32_e32 v1, v0
	v_mov_b32_e32 v2, v0
	v_mov_b32_e32 v3, v0
	v_mov_b32_e32 v4, v0
	v_mov_b32_e32 v5, v0
	v_mov_b32_e32 v6, v0
	v_mov_b32_e32 v7, v0
	v_mov_b32_e32 v16, v0
	v_mov_b32_e32 v17, v0
	v_mov_b32_e32 v18, v0
	v_mov_b32_e32 v19, v0
	v_mov_b32_e32 v20, v0
	v_mov_b32_e32 v21, v0
	v_mov_b32_e32 v22, v0
	v_mov_b32_e32 v23, v0
	v_mov_b32_e32 v32, v0
	v_mov_b32_e32 v33, v0
	v_mov_b32_e32 v34, v0
	v_mov_b32_e32 v35, v0
	v_mov_b32_e32 v36, v0
	v_mov_b32_e32 v37, v0
	v_mov_b32_e32 v38, v0
	v_mov_b32_e32 v39, v0
	v_mov_b32_e32 v48, v0
	v_mov_b32_e32 v49, v0
	v_mov_b32_e32 v50, v0
	v_mov_b32_e32 v51, v0
	v_mov_b32_e32 v52, v0
	v_mov_b32_e32 v53, v0
	v_mov_b32_e32 v54, v0
	v_mov_b32_e32 v55, v0
	v_mov_b32_e32 v8, v0
	v_mov_b32_e32 v9, v0
	v_mov_b32_e32 v10, v0
	v_mov_b32_e32 v11, v0
	v_mov_b32_e32 v12, v0
	v_mov_b32_e32 v13, v0
	v_mov_b32_e32 v14, v0
	v_mov_b32_e32 v15, v0
	v_mov_b32_e32 v24, v0
	v_mov_b32_e32 v25, v0
	v_mov_b32_e32 v26, v0
	v_mov_b32_e32 v27, v0
	v_mov_b32_e32 v28, v0
	v_mov_b32_e32 v29, v0
	v_mov_b32_e32 v30, v0
	v_mov_b32_e32 v31, v0
	v_mov_b32_e32 v40, v0
	v_mov_b32_e32 v41, v0
	v_mov_b32_e32 v42, v0
	v_mov_b32_e32 v43, v0
	v_mov_b32_e32 v44, v0
	v_mov_b32_e32 v45, v0
	v_mov_b32_e32 v46, v0
	v_mov_b32_e32 v47, v0
	v_mov_b32_e32 v56, v0
	v_mov_b32_e32 v57, v0
	v_mov_b32_e32 v58, v0
	v_mov_b32_e32 v59, v0
	v_mov_b32_e32 v60, v0
	v_mov_b32_e32 v61, v0
	v_mov_b32_e32 v62, v0
	v_mov_b32_e32 v63, v0
	v_mov_b32_e32 v64, v0
	v_mov_b32_e32 v65, v0
	v_mov_b32_e32 v66, v0
	v_mov_b32_e32 v67, v0
	v_mov_b32_e32 v68, v0
	v_mov_b32_e32 v69, v0
	v_mov_b32_e32 v70, v0
	v_mov_b32_e32 v71, v0
	v_mov_b32_e32 v80, v0
	v_mov_b32_e32 v81, v0
	v_mov_b32_e32 v82, v0
	v_mov_b32_e32 v83, v0
	v_mov_b32_e32 v84, v0
	v_mov_b32_e32 v85, v0
	v_mov_b32_e32 v86, v0
	v_mov_b32_e32 v87, v0
	v_mov_b32_e32 v96, v0
	v_mov_b32_e32 v97, v0
	v_mov_b32_e32 v98, v0
	v_mov_b32_e32 v99, v0
	v_mov_b32_e32 v100, v0
	v_mov_b32_e32 v101, v0
	v_mov_b32_e32 v102, v0
	v_mov_b32_e32 v103, v0
	v_mov_b32_e32 v116, v0
	v_mov_b32_e32 v117, v0
	v_mov_b32_e32 v118, v0
	v_mov_b32_e32 v119, v0
	v_mov_b32_e32 v120, v0
	v_mov_b32_e32 v121, v0
	v_mov_b32_e32 v122, v0
	v_mov_b32_e32 v123, v0
	v_mov_b32_e32 v72, v0
	v_mov_b32_e32 v73, v0
	v_mov_b32_e32 v74, v0
	v_mov_b32_e32 v75, v0
	v_mov_b32_e32 v76, v0
	v_mov_b32_e32 v77, v0
	v_mov_b32_e32 v78, v0
	v_mov_b32_e32 v79, v0
	v_mov_b32_e32 v88, v0
	v_mov_b32_e32 v89, v0
	v_mov_b32_e32 v90, v0
	v_mov_b32_e32 v91, v0
	v_mov_b32_e32 v92, v0
	v_mov_b32_e32 v93, v0
	v_mov_b32_e32 v94, v0
	v_mov_b32_e32 v95, v0
	v_mov_b32_e32 v104, v0
	v_mov_b32_e32 v105, v0
	v_mov_b32_e32 v106, v0
	v_mov_b32_e32 v107, v0
	v_mov_b32_e32 v108, v0
	v_mov_b32_e32 v109, v0
	v_mov_b32_e32 v110, v0
	v_mov_b32_e32 v111, v0
	v_mov_b32_e32 v124, v0
	v_mov_b32_e32 v125, v0
	v_mov_b32_e32 v126, v0
	v_mov_b32_e32 v127, v0
	v_mov_b32_e32 v128, v0
	v_mov_b32_e32 v129, v0
	v_mov_b32_e32 v130, v0
	v_mov_b32_e32 v131, v0
	.p2align 6

;     __device__ __forceinline__ bool next(int i, pg8::Unit& u) const { const int L = i * G + c; if (L >= 64) return false; u.pm = L; u.pn = L >> 5; return true; }
;     __host__ __device__ bool next(int i, Unit& u) const {
;         const long L = (long)i * G + c; if (L >= nwg) return false;
;         int wgid = (int)L; { const int q = nwg / NXCD, r = nwg % NXCD, xcd = wgid % NXCD, off = wgid / NXCD; wgid = (xcd < r ? xcd * (q + 1) : r * (q + 1) + (xcd - r) * q) + off; }
;         const int nig = WGM * nN, gid = wgid / nig, fm = gid * WGM, gsz = (nM - fm) < WGM ? (nM - fm) : WGM;
;         u.pm = fm + ((wgid % nig) % gsz); u.pn = (wgid % nig) / gsz; return true;
;     }
.LBB0_1380:
	s_ashr_i32 s1, s1, 3
	s_add_i32 s1, s13, s1
	s_ashr_i32 s10, s1, 31
	s_lshr_b32 s10, s10, 27
	s_add_i32 s10, s1, s10
	s_ashr_i32 s11, s10, 5
	s_lshl_b32 s11, s11, 3
	s_sub_i32 s12, 0x80, s11
	s_min_i32 s12, s12, 8
	s_abs_i32 s13, s12
	v_cvt_f32_u32_e32 v7, s13
	s_sub_i32 s15, 0, s13
	s_andn2_b32 s10, s10, 31
	s_sub_i32 s1, s1, s10
	v_rcp_iflag_f32_e32 v7, v7
	s_abs_i32 s10, s1
	s_xor_b32 s14, s1, s12
	s_ashr_i32 s14, s14, 31
	v_mul_f32_e32 v7, 0x4f7ffffe, v7
	v_cvt_u32_f32_e32 v7, v7
	s_nop 0
	v_readfirstlane_b32 s16, v7
	s_mul_i32 s15, s15, s16
	s_mul_hi_u32 s15, s16, s15
	s_add_i32 s16, s16, s15
	s_mul_hi_u32 s15, s10, s16
	s_mul_i32 s16, s15, s13
	s_sub_i32 s10, s10, s16
	s_add_i32 s17, s15, 1
	s_sub_i32 s16, s10, s13
	s_cmp_ge_u32 s10, s13
	s_cselect_b32 s15, s17, s15
	s_cselect_b32 s10, s16, s10
	s_add_i32 s16, s15, 1
	s_cmp_ge_u32 s10, s13
	s_cselect_b32 s10, s16, s15
	s_xor_b32 s10, s10, s14
	s_sub_i32 s10, s10, s14
	s_mul_i32 s12, s10, s12
	s_sub_i32 s1, s1, s12
	s_add_i32 s12, s11, s1
	.p2align 6

;     __device__ __forceinline__ bool next(int i, pg8::Unit& u) const { const int L = i * G + c; if (L >= 64) return false; u.pm = L; u.pn = L >> 5; return true; }
; template <class Epi, class Sched, bool ALIGN_EPI = false, bool SP2 = false>
; __device__ __forceinline__ void gemm_phase(PG8_LAS unsigned char* lds, const Gemm g, const Sched& S, const Epi& E, const int wv) {
;     ...
;     for (;;) {
;         const bool has_next = S.next(ui + 1, nxt);
;         const char* nA = has_next ? (const char*)g.A + (size_t)nxt.pm * tstepA : cA; const char* nB = has_next ? (const char*)g.Bt + (size_t)nxt.pn * tstepB : cB;
;         for (int t = 0; t < nt; t += 2) {
;             const bool last = (t == nt - 2);
;             const char* a1 = cA + (size_t)(t + 1) * kstep;
;             const char* a2 = last ? nA : cA + (size_t)(t + 2) * kstep; const char* b2 = last ? nB : cB + (size_t)(t + 2) * kstep;
;             const char* a3 = a2 + kstep; const char* b3 = b2 + kstep;
;     ...
; #pragma unroll
;         for (int a = 0; a < 2; ++a)
; #pragma unroll
;             for (int b = 0; b < 2; ++b)
; #pragma unroll
;                 for (int m = 0; m < 4; ++m)
; #pragma unroll
;                     for (int n = 0; n < 2; ++n) acc[a][b][m][n] = (f32x4){0.f, 0.f, 0.f, 0.f};
.LBB0_1464:
	s_ashr_i32 s53, s52, 31
	s_lshl_b64 s[0:1], s[52:53], 19
	s_add_u32 s54, s2, s0
	s_addc_u32 s55, s3, s1
	s_and_b64 s[0:1], s[40:41], exec
	s_cselect_b32 s0, s55, s43
	s_cselect_b32 s5, s54, s42
	s_ashr_i32 s51, s50, 31
	s_lshl_b64 s[56:57], s[50:51], 19
	s_add_u32 s56, s33, s56
	s_addc_u32 s57, s34, s57
	s_and_b64 s[58:59], s[40:41], exec
	s_cselect_b32 s47, s57, s45
	s_cselect_b32 s51, s56, s44
	s_add_u32 s42, s42, 0x40080
	s_addc_u32 s43, s43, 0
	s_add_u32 s53, s44, 0x100
	v_mov_b32_e32 v0, 0
	s_addc_u32 s70, s45, 0
	s_mov_b32 s71, -2
	v_mov_b32_e32 v1, v0
	v_mov_b32_e32 v2, v0
	v_mov_b32_e32 v3, v0
	v_mov_b32_e32 v4, v0
	v_mov_b32_e32 v5, v0
	v_mov_b32_e32 v6, v0
	v_mov_b32_e32 v7, v0
	v_mov_b32_e32 v16, v0
	v_mov_b32_e32 v17, v0
	v_mov_b32_e32 v18, v0
	v_mov_b32_e32 v19, v0
	v_mov_b32_e32 v20, v0
	v_mov_b32_e32 v21, v0
	v_mov_b32_e32 v22, v0
	v_mov_b32_e32 v23, v0
	v_mov_b32_e32 v32, v0
	v_mov_b32_e32 v33, v0
	v_mov_b32_e32 v34, v0
	v_mov_b32_e32 v35, v0
	v_mov_b32_e32 v36, v0
	v_mov_b32_e32 v37, v0
	v_mov_b32_e32 v38, v0
	v_mov_b32_e32 v39, v0
	v_mov_b32_e32 v48, v0
	v_mov_b32_e32 v49, v0
	v_mov_b32_e32 v50, v0
	v_mov_b32_e32 v51, v0
	v_mov_b32_e32 v52, v0
	v_mov_b32_e32 v53, v0
	v_mov_b32_e32 v54, v0
	v_mov_b32_e32 v55, v0
	v_mov_b32_e32 v8, v0
	v_mov_b32_e32 v9, v0
	v_mov_b32_e32 v10, v0
	v_mov_b32_e32 v11, v0
	v_mov_b32_e32 v12, v0
	v_mov_b32_e32 v13, v0
	v_mov_b32_e32 v14, v0
	v_mov_b32_e32 v15, v0
	v_mov_b32_e32 v24, v0
	v_mov_b32_e32 v25, v0
	v_mov_b32_e32 v26, v0
	v_mov_b32_e32 v27, v0
	v_mov_b32_e32 v28, v0
	v_mov_b32_e32 v29, v0
	v_mov_b32_e32 v30, v0
	v_mov_b32_e32 v31, v0
	v_mov_b32_e32 v40, v0
	v_mov_b32_e32 v41, v0
	v_mov_b32_e32 v42, v0
	v_mov_b32_e32 v43, v0
	v_mov_b32_e32 v44, v0
	v_mov_b32_e32 v45, v0
	v_mov_b32_e32 v46, v0
	v_mov_b32_e32 v47, v0
	v_mov_b32_e32 v56, v0
	v_mov_b32_e32 v57, v0
	v_mov_b32_e32 v58, v0
	v_mov_b32_e32 v59, v0
	v_mov_b32_e32 v60, v0
	v_mov_b32_e32 v61, v0
	v_mov_b32_e32 v62, v0
	v_mov_b32_e32 v63, v0
	v_mov_b32_e32 v64, v0
	v_mov_b32_e32 v65, v0
	v_mov_b32_e32 v66, v0
	v_mov_b32_e32 v67, v0
	v_mov_b32_e32 v68, v0
	v_mov_b32_e32 v69, v0
	v_mov_b32_e32 v70, v0
	v_mov_b32_e32 v71, v0
	v_mov_b32_e32 v80, v0
	v_mov_b32_e32 v81, v0
	v_mov_b32_e32 v82, v0
	v_mov_b32_e32 v83, v0
	v_mov_b32_e32 v84, v0
	v_mov_b32_e32 v85, v0
	v_mov_b32_e32 v86, v0
	v_mov_b32_e32 v87, v0
	v_mov_b32_e32 v96, v0
	v_mov_b32_e32 v97, v0
	v_mov_b32_e32 v98, v0
	v_mov_b32_e32 v99, v0
	v_mov_b32_e32 v100, v0
	v_mov_b32_e32 v101, v0
	v_mov_b32_e32 v102, v0
	v_mov_b32_e32 v103, v0
	v_mov_b32_e32 v116, v0
	v_mov_b32_e32 v117, v0
	v_mov_b32_e32 v118, v0
	v_mov_b32_e32 v119, v0
	v_mov_b32_e32 v120, v0
	v_mov_b32_e32 v121, v0
	v_mov_b32_e32 v122, v0
	v_mov_b32_e32 v123, v0
	v_mov_b32_e32 v72, v0
	v_mov_b32_e32 v73, v0
	v_mov_b32_e32 v74, v0
	v_mov_b32_e32 v75, v0
	v_mov_b32_e32 v76, v0
	v_mov_b32_e32 v77, v0
	v_mov_b32_e32 v78, v0
	v_mov_b32_e32 v79, v0
	v_mov_b32_e32 v88, v0
	v_mov_b32_e32 v89, v0
	v_mov_b32_e32 v90, v0
	v_mov_b32_e32 v91, v0
	v_mov_b32_e32 v92, v0
	v_mov_b32_e32 v93, v0
	v_mov_b32_e32 v94, v0
	v_mov_b32_e32 v95, v0
	v_mov_b32_e32 v104, v0
	v_mov_b32_e32 v105, v0
	v_mov_b32_e32 v106, v0
	v_mov_b32_e32 v107, v0
	v_mov_b32_e32 v108, v0
	v_mov_b32_e32 v109, v0
	v_mov_b32_e32 v110, v0
	v_mov_b32_e32 v111, v0
	v_mov_b32_e32 v124, v0
	v_mov_b32_e32 v125, v0
	v_mov_b32_e32 v126, v0
	v_mov_b32_e32 v127, v0
	v_mov_b32_e32 v128, v0
	v_mov_b32_e32 v129, v0
	v_mov_b32_e32 v130, v0
	v_mov_b32_e32 v131, v0
	.p2align 6
